# P3 LPT order table built at the end of P2 by the 240 non-cumsum workgroups (UINFO written through + counted); static tickets reversed so the late cumsum workgroups take the cheapest static units
# baseline (speedup 1.0000x reference)
.LBB0_199:
	s_or_b64 exec, exec, s[4:5]
	v_lshl_add_u32 v0, s2, 5, v18
	v_ashrrev_i32_e32 v1, 31, v0
	v_lshl_add_u64 v[0:1], v[0:1], 2, s[88:89]
	v_add_co_u32_e32 v0, vcc, 0x80000, v0
	s_nop 1
	v_addc_co_u32_e32 v1, vcc, 0, v1, vcc
	global_store_dword v[0:1], v2, off sc0 sc1
	s_waitcnt vmcnt(0)
	v_mov_b32_e32 v3, 0xe040
	v_mov_b32_e32 v4, 1
	global_atomic_add v3, v4, s[88:89]

.LBB0_260:
	s_mov_b32 s101, 0
	s_cmp_gt_i32 s91, 3
	s_cselect_b64 s[0:1], -1, 0
	s_and_b64 s[4:5], s[6:7], s[0:1]
	s_andn2_b64 vcc, exec, s[4:5]
	s_cbranch_vccnz .LBB0_314
	s_waitcnt vmcnt(0)
	s_waitcnt vmcnt(0)
	s_cmp_lt_u32 s2, 16
	s_cbranch_scc1 .Ler_skip
	s_cmpk_lg_u32 s33, 0x100
	s_cbranch_scc1 .Ler_skip
	s_waitcnt lgkmcnt(0)
	s_barrier
	v_mov_b32_e32 v8, 0xe040
.Ler_poll:
	global_load_dword v9, v8, s[88:89] sc1
	s_waitcnt vmcnt(0)
	v_readfirstlane_b32 s3, v9
	s_cmpk_lt_u32 s3, 0x200
	s_cbranch_scc1 .Ler_poll
	v_mov_b32_e32 v0, v254
	v_lshlrev_b32_e32 v2, 2, v0
	v_add_u32_e32 v3, 0x80000, v2
	global_load_dword v1, v3, s[88:89] sc1
	v_and_b32_e32 v3, 0x7c, v2
	v_add_u32_e32 v2, 0x1e000, v2
	s_waitcnt vmcnt(0)
	v_sub_u32_e32 v1, v3, v1
	v_add_u32_e32 v1, 4, v1
	ds_write_b32 v2, v1
	v_lshlrev_b32_e32 v3, 9, v1
	v_sub_u32_e32 v6, 0x1ff, v0
	v_add_u32_e32 v3, v3, v6
	ds_write_b32 v2, v3 offset:8192
	s_waitcnt lgkmcnt(0)
	s_barrier
	v_mov_b32_e32 v4, 0
	v_mov_b32_e32 v5, 0
	v_mov_b32_e32 v7, 0x20000
	ds_read_b128 v[8:11], v7
	ds_read_b128 v[12:15], v7 offset:16
	ds_read_b128 v[16:19], v7 offset:32
	ds_read_b128 v[20:23], v7 offset:48
	ds_read_b128 v[24:27], v7 offset:64
	ds_read_b128 v[28:31], v7 offset:80
	ds_read_b128 v[32:35], v7 offset:96
	ds_read_b128 v[36:39], v7 offset:112
	s_mov_b32 s3, 8
.Ler_rank_loop:
	ds_read_b128 v[40:43], v7 offset:128
	ds_read_b128 v[44:47], v7 offset:144
	ds_read_b128 v[48:51], v7 offset:160
	ds_read_b128 v[52:55], v7 offset:176
	ds_read_b128 v[56:59], v7 offset:192
	ds_read_b128 v[60:63], v7 offset:208
	ds_read_b128 v[64:67], v7 offset:224
	ds_read_b128 v[68:71], v7 offset:240
	s_waitcnt lgkmcnt(8)
	v_cmp_lt_u32_e64 s[6:7], v3, v8
	v_cmp_lt_u32_e64 s[8:9], v3, v9
	v_cmp_lt_u32_e64 s[10:11], v3, v10
	v_cmp_lt_u32_e64 s[12:13], v3, v11
	v_addc_co_u32_e64 v4, vcc, 0, v4, s[6:7]
	v_addc_co_u32_e64 v5, vcc, 0, v5, s[8:9]
	v_addc_co_u32_e64 v4, vcc, 0, v4, s[10:11]
	v_addc_co_u32_e64 v5, vcc, 0, v5, s[12:13]
	v_cmp_lt_u32_e64 s[6:7], v3, v12
	v_cmp_lt_u32_e64 s[8:9], v3, v13
	v_cmp_lt_u32_e64 s[10:11], v3, v14
	v_cmp_lt_u32_e64 s[12:13], v3, v15
	v_addc_co_u32_e64 v4, vcc, 0, v4, s[6:7]
	v_addc_co_u32_e64 v5, vcc, 0, v5, s[8:9]
	v_addc_co_u32_e64 v4, vcc, 0, v4, s[10:11]
	v_addc_co_u32_e64 v5, vcc, 0, v5, s[12:13]
	v_cmp_lt_u32_e64 s[6:7], v3, v16
	v_cmp_lt_u32_e64 s[8:9], v3, v17
	v_cmp_lt_u32_e64 s[10:11], v3, v18
	v_cmp_lt_u32_e64 s[12:13], v3, v19
	v_addc_co_u32_e64 v4, vcc, 0, v4, s[6:7]
	v_addc_co_u32_e64 v5, vcc, 0, v5, s[8:9]
	v_addc_co_u32_e64 v4, vcc, 0, v4, s[10:11]
	v_addc_co_u32_e64 v5, vcc, 0, v5, s[12:13]
	v_cmp_lt_u32_e64 s[6:7], v3, v20
	v_cmp_lt_u32_e64 s[8:9], v3, v21
	v_cmp_lt_u32_e64 s[10:11], v3, v22
	v_cmp_lt_u32_e64 s[12:13], v3, v23
	v_addc_co_u32_e64 v4, vcc, 0, v4, s[6:7]
	v_addc_co_u32_e64 v5, vcc, 0, v5, s[8:9]
	v_addc_co_u32_e64 v4, vcc, 0, v4, s[10:11]
	v_addc_co_u32_e64 v5, vcc, 0, v5, s[12:13]
	v_cmp_lt_u32_e64 s[6:7], v3, v24
	v_cmp_lt_u32_e64 s[8:9], v3, v25
	v_cmp_lt_u32_e64 s[10:11], v3, v26
	v_cmp_lt_u32_e64 s[12:13], v3, v27
	v_addc_co_u32_e64 v4, vcc, 0, v4, s[6:7]
	v_addc_co_u32_e64 v5, vcc, 0, v5, s[8:9]
	v_addc_co_u32_e64 v4, vcc, 0, v4, s[10:11]
	v_addc_co_u32_e64 v5, vcc, 0, v5, s[12:13]
	v_cmp_lt_u32_e64 s[6:7], v3, v28
	v_cmp_lt_u32_e64 s[8:9], v3, v29
	v_cmp_lt_u32_e64 s[10:11], v3, v30
	v_cmp_lt_u32_e64 s[12:13], v3, v31
	v_addc_co_u32_e64 v4, vcc, 0, v4, s[6:7]
	v_addc_co_u32_e64 v5, vcc, 0, v5, s[8:9]
	v_addc_co_u32_e64 v4, vcc, 0, v4, s[10:11]
	v_addc_co_u32_e64 v5, vcc, 0, v5, s[12:13]
	v_cmp_lt_u32_e64 s[6:7], v3, v32
	v_cmp_lt_u32_e64 s[8:9], v3, v33
	v_cmp_lt_u32_e64 s[10:11], v3, v34
	v_cmp_lt_u32_e64 s[12:13], v3, v35
	v_addc_co_u32_e64 v4, vcc, 0, v4, s[6:7]
	v_addc_co_u32_e64 v5, vcc, 0, v5, s[8:9]
	v_addc_co_u32_e64 v4, vcc, 0, v4, s[10:11]
	v_addc_co_u32_e64 v5, vcc, 0, v5, s[12:13]
	v_cmp_lt_u32_e64 s[6:7], v3, v36
	v_cmp_lt_u32_e64 s[8:9], v3, v37
	v_cmp_lt_u32_e64 s[10:11], v3, v38
	v_cmp_lt_u32_e64 s[12:13], v3, v39
	v_addc_co_u32_e64 v4, vcc, 0, v4, s[6:7]
	v_addc_co_u32_e64 v5, vcc, 0, v5, s[8:9]
	v_addc_co_u32_e64 v4, vcc, 0, v4, s[10:11]
	v_addc_co_u32_e64 v5, vcc, 0, v5, s[12:13]
	v_add_u32_e32 v7, 0x100, v7
	ds_read_b128 v[8:11], v7
	ds_read_b128 v[12:15], v7 offset:16
	ds_read_b128 v[16:19], v7 offset:32
	ds_read_b128 v[20:23], v7 offset:48
	ds_read_b128 v[24:27], v7 offset:64
	ds_read_b128 v[28:31], v7 offset:80
	ds_read_b128 v[32:35], v7 offset:96
	ds_read_b128 v[36:39], v7 offset:112
	s_waitcnt lgkmcnt(8)
	v_cmp_lt_u32_e64 s[6:7], v3, v40
	v_cmp_lt_u32_e64 s[8:9], v3, v41
	v_cmp_lt_u32_e64 s[10:11], v3, v42
	v_cmp_lt_u32_e64 s[12:13], v3, v43
	v_addc_co_u32_e64 v4, vcc, 0, v4, s[6:7]
	v_addc_co_u32_e64 v5, vcc, 0, v5, s[8:9]
	v_addc_co_u32_e64 v4, vcc, 0, v4, s[10:11]
	v_addc_co_u32_e64 v5, vcc, 0, v5, s[12:13]
	v_cmp_lt_u32_e64 s[6:7], v3, v44
	v_cmp_lt_u32_e64 s[8:9], v3, v45
	v_cmp_lt_u32_e64 s[10:11], v3, v46
	v_cmp_lt_u32_e64 s[12:13], v3, v47
	v_addc_co_u32_e64 v4, vcc, 0, v4, s[6:7]
	v_addc_co_u32_e64 v5, vcc, 0, v5, s[8:9]
	v_addc_co_u32_e64 v4, vcc, 0, v4, s[10:11]
	v_addc_co_u32_e64 v5, vcc, 0, v5, s[12:13]
	v_cmp_lt_u32_e64 s[6:7], v3, v48
	v_cmp_lt_u32_e64 s[8:9], v3, v49
	v_cmp_lt_u32_e64 s[10:11], v3, v50
	v_cmp_lt_u32_e64 s[12:13], v3, v51
	v_addc_co_u32_e64 v4, vcc, 0, v4, s[6:7]
	v_addc_co_u32_e64 v5, vcc, 0, v5, s[8:9]
	v_addc_co_u32_e64 v4, vcc, 0, v4, s[10:11]
	v_addc_co_u32_e64 v5, vcc, 0, v5, s[12:13]
	v_cmp_lt_u32_e64 s[6:7], v3, v52
	v_cmp_lt_u32_e64 s[8:9], v3, v53
	v_cmp_lt_u32_e64 s[10:11], v3, v54
	v_cmp_lt_u32_e64 s[12:13], v3, v55
	v_addc_co_u32_e64 v4, vcc, 0, v4, s[6:7]
	v_addc_co_u32_e64 v5, vcc, 0, v5, s[8:9]
	v_addc_co_u32_e64 v4, vcc, 0, v4, s[10:11]
	v_addc_co_u32_e64 v5, vcc, 0, v5, s[12:13]
	v_cmp_lt_u32_e64 s[6:7], v3, v56
	v_cmp_lt_u32_e64 s[8:9], v3, v57
	v_cmp_lt_u32_e64 s[10:11], v3, v58
	v_cmp_lt_u32_e64 s[12:13], v3, v59
	v_addc_co_u32_e64 v4, vcc, 0, v4, s[6:7]
	v_addc_co_u32_e64 v5, vcc, 0, v5, s[8:9]
	v_addc_co_u32_e64 v4, vcc, 0, v4, s[10:11]
	v_addc_co_u32_e64 v5, vcc, 0, v5, s[12:13]
	v_cmp_lt_u32_e64 s[6:7], v3, v60
	v_cmp_lt_u32_e64 s[8:9], v3, v61
	v_cmp_lt_u32_e64 s[10:11], v3, v62
	v_cmp_lt_u32_e64 s[12:13], v3, v63
	v_addc_co_u32_e64 v4, vcc, 0, v4, s[6:7]
	v_addc_co_u32_e64 v5, vcc, 0, v5, s[8:9]
	v_addc_co_u32_e64 v4, vcc, 0, v4, s[10:11]
	v_addc_co_u32_e64 v5, vcc, 0, v5, s[12:13]
	v_cmp_lt_u32_e64 s[6:7], v3, v64
	v_cmp_lt_u32_e64 s[8:9], v3, v65
	v_cmp_lt_u32_e64 s[10:11], v3, v66
	v_cmp_lt_u32_e64 s[12:13], v3, v67
	v_addc_co_u32_e64 v4, vcc, 0, v4, s[6:7]
	v_addc_co_u32_e64 v5, vcc, 0, v5, s[8:9]
	v_addc_co_u32_e64 v4, vcc, 0, v4, s[10:11]
	v_addc_co_u32_e64 v5, vcc, 0, v5, s[12:13]
	v_cmp_lt_u32_e64 s[6:7], v3, v68
	v_cmp_lt_u32_e64 s[8:9], v3, v69
	v_cmp_lt_u32_e64 s[10:11], v3, v70
	v_cmp_lt_u32_e64 s[12:13], v3, v71
	v_addc_co_u32_e64 v4, vcc, 0, v4, s[6:7]
	v_addc_co_u32_e64 v5, vcc, 0, v5, s[8:9]
	v_addc_co_u32_e64 v4, vcc, 0, v4, s[10:11]
	v_addc_co_u32_e64 v5, vcc, 0, v5, s[12:13]
	s_sub_i32 s3, s3, 1
	s_cmp_lg_u32 s3, 0
	s_cbranch_scc1 .Ler_rank_loop
	s_waitcnt lgkmcnt(0)
	v_add_u32_e32 v1, v5, v4
	v_lshl_add_u32 v1, v1, 2, 0
	v_add_u32_e32 v1, 0x1e800, v1
	ds_write_b32 v1, v0
	s_waitcnt lgkmcnt(0)
	s_mov_b32 s101, 1
.Ler_skip:
	s_barrier
	s_and_saveexec_b64 s[4:5], s[84:85]
	s_cbranch_execz .LBB0_313
	s_add_i32 s3, 0, 0x23c00
	v_mov_b32_e32 v0, s3
	s_waitcnt vmcnt(0) expcnt(0) lgkmcnt(0)
	ds_read_b32 v2, v0
	s_add_i32 s3, 0, 0x23c04
	v_mov_b32_e32 v0, s3
	ds_read_b32 v0, v0
	s_waitcnt lgkmcnt(1)
	v_cmp_ne_u32_e32 vcc, 0, v2
	s_cbranch_vccnz .LBB0_277
	v_readlane_b32 s6, v255, 0
	v_readlane_b32 s7, v255, 1
	s_load_dwordx2 s[10:11], s[6:7], 0x4
	s_add_u32 s6, s88, 0x10200
	s_addc_u32 s7, s89, 0
	s_add_u32 s8, s88, 0x10400
	s_addc_u32 s9, s89, 0
	s_waitcnt lgkmcnt(0)
	s_mul_i32 s3, s10, s33
	s_add_u32 s10, s88, 0x10500
	s_mul_i32 s3, s3, s11
	s_addc_u32 s11, s89, 0
	s_add_u32 s12, s88, 0x10600
	s_addc_u32 s13, s89, 0
	s_add_u32 s16, s88, 0x10700
	s_addc_u32 s17, s89, 0
	s_add_u32 s18, s88, 0x10800
	s_addc_u32 s19, s89, 0
	s_add_u32 s20, s88, 0x10900
	s_addc_u32 s21, s89, 0
	s_add_u32 s22, s88, 0x10a00
	s_addc_u32 s23, s89, 0
	s_add_u32 s24, s88, 0x10b00
	s_addc_u32 s25, s89, 0
	s_add_u32 s26, s88, 0x10c00
	s_addc_u32 s27, s89, 0
	s_add_u32 s28, s88, 0x10d00
	s_addc_u32 s29, s89, 0
	s_add_u32 s30, s88, 0x10e00
	s_addc_u32 s31, s89, 0
	s_add_u32 s34, s88, 0x10f00
	s_addc_u32 s35, s89, 0
	s_add_u32 s36, s88, 0x11000
	s_addc_u32 s37, s89, 0
	s_add_u32 s38, s88, 0x11100
	s_addc_u32 s39, s89, 0
	s_add_u32 s40, s88, 0x11200
	s_addc_u32 s41, s89, 0
	s_add_u32 s42, s88, 0x11300
	s_addc_u32 s43, s89, 0
	s_mov_b32 s50, 1
	v_mov_b32_e32 v16, 0
	s_branch .LBB0_265

.LBB0_314:
	s_cmp_lt_i32 s90, 4
	s_cselect_b64 s[4:5], -1, 0
	s_and_b64 s[62:63], s[4:5], s[0:1]
	s_andn2_b64 vcc, exec, s[62:63]
	s_mov_b32 s3, 1
	s_cbranch_vccnz .LBB0_430
	s_cmp_eq_u32 s101, 0
	s_cbranch_scc1 .Ler_do_rank
	s_mov_b32 s64, 0
	s_mov_b32 s65, 0
	v_lshlrev_b32_e32 v2, 3, v254
	s_branch .Ler_have_rank
.Ler_do_rank:
	v_mov_b32_e32 v0, v254
	s_mov_b32 s64, 0
	v_ashrrev_i32_e32 v1, 31, v0
	v_lshl_add_u64 v[2:3], v[0:1], 2, s[88:89]
	v_add_co_u32_e32 v2, vcc, 0x80000, v2
	v_mov_b32_e32 v5, 0
	s_nop 0
	v_addc_co_u32_e32 v3, vcc, 0, v3, vcc
	global_load_dword v1, v[2:3], off
	v_lshlrev_b32_e32 v2, 2, v0
	v_and_b32_e32 v3, 0x7c, v2
	v_add_u32_e32 v2, 0, v2
	v_add_u32_e32 v2, 0x1e000, v2
	v_mov_b32_e32 v4, 0
	s_mov_b32 s65, 0
	s_waitcnt vmcnt(0)
	v_sub_u32_e32 v1, v3, v1
	v_add_u32_e32 v1, 4, v1
	ds_write_b32 v2, v1
	v_lshlrev_b32_e32 v3, 9, v1
	v_sub_u32_e32 v6, 0x1ff, v0
	v_add_u32_e32 v3, v3, v6
	ds_write_b32 v2, v3 offset:8192
	s_waitcnt lgkmcnt(0)
	s_barrier
	v_mov_b32_e32 v4, 0
	v_mov_b32_e32 v5, 0
	v_mov_b32_e32 v7, 0x20000
	ds_read_b128 v[8:11], v7
	ds_read_b128 v[12:15], v7 offset:16
	ds_read_b128 v[16:19], v7 offset:32
	ds_read_b128 v[20:23], v7 offset:48
	ds_read_b128 v[24:27], v7 offset:64
	ds_read_b128 v[28:31], v7 offset:80
	ds_read_b128 v[32:35], v7 offset:96
	ds_read_b128 v[36:39], v7 offset:112
	s_mov_b32 s10, 8

.Ler_have_rank:
	v_lshlrev_b32_e32 v0, 7, v254
	v_and_b32_e32 v3, 24, v2
	s_movk_i32 s0, 0x1e00
	s_add_u32 s3, s88, 0x7200000
	v_and_or_b32 v0, v0, s0, v3
	s_addc_u32 s26, s89, 0
	v_and_b32_e32 v209, 31, v254
	v_bfe_u32 v210, v254, 5, 1
	v_lshlrev_b32_e32 v212, 1, v0
	v_lshlrev_b32_e32 v0, 1, v254
	s_add_u32 s27, s88, 0x8200000
	v_and_b32_e32 v1, 63, v254
	v_lshlrev_b32_e32 v4, 10, v210
	v_lshlrev_b32_e32 v5, 4, v209
	v_and_b32_e32 v0, 32, v0
	v_lshlrev_b32_e32 v194, 4, v254
	s_addc_u32 s28, s89, 0
	v_lshlrev_b32_e32 v211, 10, v1
	v_add3_u32 v3, 0, v0, v3
	v_lshlrev_b32_e32 v6, 8, v210
	v_add3_u32 v213, 0, v4, v5
	v_and_b32_e32 v4, 0xc0, v194
	v_cmp_gt_u32_e64 s[4:5], 32, v1
	v_bfe_u32 v1, v254, 3, 3
	s_add_u32 s29, s88, 0x9200000
	v_add3_u32 v214, v3, v6, v4
	v_or_b32_e32 v3, 8, v1
	s_addc_u32 s30, s89, 0
	v_lshlrev_b32_e32 v0, 9, v209
	v_mov_b32_e32 v195, 0
	v_lshlrev_b32_e32 v247, 7, v1
	v_lshlrev_b32_e32 v4, 10, v1
	v_lshlrev_b32_e32 v248, 7, v3
	v_lshlrev_b32_e32 v6, 10, v3
	v_or_b32_e32 v3, 16, v1
	v_or_b32_e32 v1, 24, v1
	s_add_u32 s31, s88, 0x2200400
	v_lshl_or_b32 v0, v210, 3, v0
	v_lshlrev_b32_e32 v215, 2, v210
	v_and_b32_e32 v2, 56, v2
	v_lshlrev_b32_e32 v8, 10, v3
	v_lshlrev_b32_e32 v250, 7, v1
	v_lshlrev_b32_e32 v10, 10, v1
	v_add_u32_e32 v1, 0, v194
	v_lshl_add_u64 v[12:13], s[88:89], 0, v[194:195]
	s_mov_b64 s[0:1], 0x180000
	s_mov_b32 s7, 0
	s_addc_u32 s34, s89, 0
	v_lshlrev_b32_e32 v216, 4, v210
	v_or_b32_e32 v217, 0xc0, v215
	v_or_b32_e32 v218, 0xc2, v215
	v_or_b32_e32 v219, 0xe2, v215
	v_or_b32_e32 v220, 0xc3, v215
	v_or_b32_e32 v221, 0xe3, v215
	v_or_b32_e32 v222, 0xc8, v215
	v_or_b32_e32 v223, 0xe8, v215
	v_or_b32_e32 v224, 0xc9, v215
	v_or_b32_e32 v225, 0xe9, v215
	v_or_b32_e32 v226, 0xca, v215
	v_or_b32_e32 v227, 0xea, v215
	v_or_b32_e32 v228, 0xcb, v215
	v_or_b32_e32 v229, 0xeb, v215
	v_or_b32_e32 v230, 0xd0, v215
	v_or_b32_e32 v231, 0xf0, v215
	v_or_b32_e32 v232, 0xd1, v215
	v_or_b32_e32 v233, 0xf1, v215
	v_or_b32_e32 v234, 0xd2, v215
	v_or_b32_e32 v235, 0xf2, v215
	v_or_b32_e32 v236, 0xd3, v215
	v_or_b32_e32 v237, 0xf3, v215
	v_or_b32_e32 v238, 0xd8, v215
	v_or_b32_e32 v239, 0xf8, v215
	v_or_b32_e32 v240, 0xd9, v215
	v_or_b32_e32 v241, 0xf9, v215
	v_or_b32_e32 v242, 0xda, v215
	v_or_b32_e32 v243, 0xfa, v215
	v_or_b32_e32 v244, 0xdb, v215
	v_or_b32_e32 v245, 0xfb, v215
	v_lshlrev_b32_e32 v246, 9, v210
	v_mov_b32_e32 v252, v254
	v_lshlrev_b32_e32 v249, 7, v3
	v_add_u32_e32 v251, 0x15400, v1
	v_lshl_add_u64 v[196:197], v[12:13], 0, s[0:1]
	v_lshlrev_b32_e32 v253, 1, v0
	s_mov_b64 s[8:9], 0x2000
	s_mov_b32 s35, 0x41a00000
	v_lshlrev_b32_e32 v194, 1, v2
	v_lshlrev_b32_e32 v198, 1, v4
	v_lshlrev_b32_e32 v200, 1, v6
	v_lshlrev_b32_e32 v202, 1, v8
	v_lshlrev_b32_e32 v204, 1, v10
	s_add_i32 s36, 0, 0x1f000
	v_mov_b32_e32 v254, 0xff800000
	s_sub_i32 s6, s33, s2
	s_add_i32 s6, s6, -1
	s_waitcnt lgkmcnt(0)
	s_barrier
	s_mov_b32 s32, 0
	s_branch .LBB0_321
